# v26 variant: read-out dots before the per-step wait, operand reads in all three DPP gaps, paired V reads and q writes kept
# speedup vs baseline: 1.0036x; 1.0036x over previous
.LBB0_1238:
	s_or_b64 exec, exec, s[18:19]
	s_waitcnt lgkmcnt(0)
	s_barrier
	s_cmp_lg_u32 s100, 0
	s_cselect_b32 s97, 0x800, 0
	v_add_u32_e32 v167, s97, v114
	ds_read_b128 v[72:75], v114 offset:41216
	ds_read_b128 v[68:71], v114 offset:45312
	ds_read_b128 v[64:67], v114 offset:49408
	ds_read_b128 v[56:59], v114 offset:53504
	ds_read_b128 v[60:63], v167 offset:28928
	ds_read2st64_b32 v[214:215], v115 offset1:1
	s_waitcnt lgkmcnt(0)
	v_dot2_f32_f16 v151, v127, v72, 0
	v_dot2_f32_f16 v151, v126, v73, v151
	v_dot2_f32_f16 v151, v125, v74, v151
	v_dot2_f32_f16 v151, v124, v75, v151
	ds_read_b128 v[134:137], v114 offset:41344
	ds_read_b128 v[138:141], v114 offset:45440
	ds_read_b128 v[142:145], v114 offset:49536
	v_add_f32_dpp v151, v151, v151 quad_perm:[1,0,3,2] row_mask:0xf bank_mask:0xf bound_ctrl:1
	ds_read_b128 v[130:133], v167 offset:29056
	ds_read_b128 v[146:149], v114 offset:53632
	v_add_f32_dpp v151, v151, v151 quad_perm:[2,3,0,1] row_mask:0xf bank_mask:0xf bound_ctrl:1
	s_nop 1
	v_add_f32_dpp v151, v151, v151 row_half_mirror row_mask:0xf bank_mask:0xf bound_ctrl:1
	v_cvt_pkrtz_f16_f32 v152, -v151, -v151
	v_pk_mul_f16 v153, v152, v68
	v_pk_mul_f16 v154, v152, v69
	v_pk_mul_f16 v155, v152, v70
	v_pk_mul_f16 v156, v152, v71
	v_pk_fma_f16 v153, v214, v64, v153
	v_pk_fma_f16 v154, v214, v65, v154
	v_pk_fma_f16 v155, v214, v66, v155
	v_pk_fma_f16 v156, v214, v67, v156
	v_pk_fma_f16 v127, v127, v60, v153
	v_pk_fma_f16 v126, v126, v61, v154
	v_pk_fma_f16 v125, v125, v62, v155
	v_pk_fma_f16 v124, v124, v63, v156
	v_dot2_f32_f16 v157, v127, v56, 0
	v_dot2_f32_f16 v157, v126, v57, v157
	v_dot2_f32_f16 v157, v125, v58, v157
	v_dot2_f32_f16 v157, v124, v59, v157
	s_waitcnt lgkmcnt(0)
	v_dot2_f32_f16 v151, v127, v134, 0
	v_dot2_f32_f16 v151, v126, v135, v151
	v_dot2_f32_f16 v151, v125, v136, v151
	v_dot2_f32_f16 v151, v124, v137, v151
	ds_read_b128 v[72:75], v114 offset:41472
	ds_read_b128 v[68:71], v114 offset:45568
	ds_read_b128 v[64:67], v114 offset:49664
	v_add_f32_dpp v151, v151, v151 quad_perm:[1,0,3,2] row_mask:0xf bank_mask:0xf bound_ctrl:1
	ds_read_b128 v[60:63], v167 offset:29184
	ds_read_b128 v[56:59], v114 offset:53760
	v_add_f32_dpp v151, v151, v151 quad_perm:[2,3,0,1] row_mask:0xf bank_mask:0xf bound_ctrl:1
	ds_read2st64_b32 v[216:217], v115 offset0:2 offset1:3
	s_nop 0
	v_add_f32_dpp v151, v151, v151 row_half_mirror row_mask:0xf bank_mask:0xf bound_ctrl:1
	v_cvt_pkrtz_f16_f32 v152, -v151, -v151
	v_pk_mul_f16 v153, v152, v138
	v_pk_mul_f16 v154, v152, v139
	v_pk_mul_f16 v155, v152, v140
	v_pk_mul_f16 v156, v152, v141
	v_pk_fma_f16 v153, v215, v142, v153
	v_pk_fma_f16 v154, v215, v143, v154
	v_pk_fma_f16 v155, v215, v144, v155
	v_pk_fma_f16 v156, v215, v145, v156
	v_pk_fma_f16 v127, v127, v130, v153
	v_pk_fma_f16 v126, v126, v131, v154
	v_pk_fma_f16 v125, v125, v132, v155
	v_pk_fma_f16 v124, v124, v133, v156
	v_dot2_f32_f16 v158, v127, v146, 0
	v_dot2_f32_f16 v158, v126, v147, v158
	v_dot2_f32_f16 v158, v125, v148, v158
	v_dot2_f32_f16 v158, v124, v149, v158
	s_waitcnt lgkmcnt(0)
	v_dot2_f32_f16 v151, v127, v72, 0
	v_dot2_f32_f16 v151, v126, v73, v151
	v_dot2_f32_f16 v151, v125, v74, v151
	v_dot2_f32_f16 v151, v124, v75, v151
	ds_read_b128 v[134:137], v114 offset:41600
	ds_read_b128 v[138:141], v114 offset:45696
	ds_read_b128 v[142:145], v114 offset:49792
	v_add_f32_dpp v151, v151, v151 quad_perm:[1,0,3,2] row_mask:0xf bank_mask:0xf bound_ctrl:1
	ds_read_b128 v[130:133], v167 offset:29312
	ds_read_b128 v[146:149], v114 offset:53888
	v_add_f32_dpp v151, v151, v151 quad_perm:[2,3,0,1] row_mask:0xf bank_mask:0xf bound_ctrl:1
	ds_write2st64_b32 v116, v157, v158 offset0:0 offset1:8
	s_nop 0
	v_add_f32_dpp v151, v151, v151 row_half_mirror row_mask:0xf bank_mask:0xf bound_ctrl:1
	v_cvt_pkrtz_f16_f32 v152, -v151, -v151
	v_pk_mul_f16 v153, v152, v68
	v_pk_mul_f16 v154, v152, v69
	v_pk_mul_f16 v155, v152, v70
	v_pk_mul_f16 v156, v152, v71
	v_pk_fma_f16 v153, v216, v64, v153
	v_pk_fma_f16 v154, v216, v65, v154
	v_pk_fma_f16 v155, v216, v66, v155
	v_pk_fma_f16 v156, v216, v67, v156
	v_pk_fma_f16 v127, v127, v60, v153
	v_pk_fma_f16 v126, v126, v61, v154
	v_pk_fma_f16 v125, v125, v62, v155
	v_pk_fma_f16 v124, v124, v63, v156
	v_dot2_f32_f16 v157, v127, v56, 0
	v_dot2_f32_f16 v157, v126, v57, v157
	v_dot2_f32_f16 v157, v125, v58, v157
	v_dot2_f32_f16 v157, v124, v59, v157
	s_waitcnt lgkmcnt(0)
	v_dot2_f32_f16 v151, v127, v134, 0
	v_dot2_f32_f16 v151, v126, v135, v151
	v_dot2_f32_f16 v151, v125, v136, v151
	v_dot2_f32_f16 v151, v124, v137, v151
	ds_read_b128 v[72:75], v114 offset:41728
	ds_read_b128 v[68:71], v114 offset:45824
	ds_read_b128 v[64:67], v114 offset:49920
	v_add_f32_dpp v151, v151, v151 quad_perm:[1,0,3,2] row_mask:0xf bank_mask:0xf bound_ctrl:1
	ds_read_b128 v[60:63], v167 offset:29440
	ds_read_b128 v[56:59], v114 offset:54016
	v_add_f32_dpp v151, v151, v151 quad_perm:[2,3,0,1] row_mask:0xf bank_mask:0xf bound_ctrl:1
	ds_read2st64_b32 v[214:215], v115 offset0:4 offset1:5
	s_nop 0
	v_add_f32_dpp v151, v151, v151 row_half_mirror row_mask:0xf bank_mask:0xf bound_ctrl:1
	v_cvt_pkrtz_f16_f32 v152, -v151, -v151
	v_pk_mul_f16 v153, v152, v138
	v_pk_mul_f16 v154, v152, v139
	v_pk_mul_f16 v155, v152, v140
	v_pk_mul_f16 v156, v152, v141
	v_pk_fma_f16 v153, v217, v142, v153
	v_pk_fma_f16 v154, v217, v143, v154
	v_pk_fma_f16 v155, v217, v144, v155
	v_pk_fma_f16 v156, v217, v145, v156
	v_pk_fma_f16 v127, v127, v130, v153
	v_pk_fma_f16 v126, v126, v131, v154
	v_pk_fma_f16 v125, v125, v132, v155
	v_pk_fma_f16 v124, v124, v133, v156
	v_dot2_f32_f16 v158, v127, v146, 0
	v_dot2_f32_f16 v158, v126, v147, v158
	v_dot2_f32_f16 v158, v125, v148, v158
	v_dot2_f32_f16 v158, v124, v149, v158
	s_waitcnt lgkmcnt(0)
	v_dot2_f32_f16 v151, v127, v72, 0
	v_dot2_f32_f16 v151, v126, v73, v151
	v_dot2_f32_f16 v151, v125, v74, v151
	v_dot2_f32_f16 v151, v124, v75, v151
	ds_read_b128 v[134:137], v114 offset:41856
	ds_read_b128 v[138:141], v114 offset:45952
	ds_read_b128 v[142:145], v114 offset:50048
	v_add_f32_dpp v151, v151, v151 quad_perm:[1,0,3,2] row_mask:0xf bank_mask:0xf bound_ctrl:1
	ds_read_b128 v[130:133], v167 offset:29568
	ds_read_b128 v[146:149], v114 offset:54144
	v_add_f32_dpp v151, v151, v151 quad_perm:[2,3,0,1] row_mask:0xf bank_mask:0xf bound_ctrl:1
	ds_write2st64_b32 v116, v157, v158 offset0:16 offset1:24
	s_nop 0
	v_add_f32_dpp v151, v151, v151 row_half_mirror row_mask:0xf bank_mask:0xf bound_ctrl:1
	v_cvt_pkrtz_f16_f32 v152, -v151, -v151
	v_pk_mul_f16 v153, v152, v68
	v_pk_mul_f16 v154, v152, v69
	v_pk_mul_f16 v155, v152, v70
	v_pk_mul_f16 v156, v152, v71
	v_pk_fma_f16 v153, v214, v64, v153
	v_pk_fma_f16 v154, v214, v65, v154
	v_pk_fma_f16 v155, v214, v66, v155
	v_pk_fma_f16 v156, v214, v67, v156
	v_pk_fma_f16 v127, v127, v60, v153
	v_pk_fma_f16 v126, v126, v61, v154
	v_pk_fma_f16 v125, v125, v62, v155
	v_pk_fma_f16 v124, v124, v63, v156
	v_dot2_f32_f16 v157, v127, v56, 0
	v_dot2_f32_f16 v157, v126, v57, v157
	v_dot2_f32_f16 v157, v125, v58, v157
	v_dot2_f32_f16 v157, v124, v59, v157
	s_waitcnt lgkmcnt(0)
	v_dot2_f32_f16 v151, v127, v134, 0
	v_dot2_f32_f16 v151, v126, v135, v151
	v_dot2_f32_f16 v151, v125, v136, v151
	v_dot2_f32_f16 v151, v124, v137, v151
	ds_read_b128 v[72:75], v114 offset:41984
	ds_read_b128 v[68:71], v114 offset:46080
	ds_read_b128 v[64:67], v114 offset:50176
	v_add_f32_dpp v151, v151, v151 quad_perm:[1,0,3,2] row_mask:0xf bank_mask:0xf bound_ctrl:1
	ds_read_b128 v[60:63], v167 offset:29696
	ds_read_b128 v[56:59], v114 offset:54272
	v_add_f32_dpp v151, v151, v151 quad_perm:[2,3,0,1] row_mask:0xf bank_mask:0xf bound_ctrl:1
	ds_read2st64_b32 v[216:217], v115 offset0:6 offset1:7
	s_nop 0
	v_add_f32_dpp v151, v151, v151 row_half_mirror row_mask:0xf bank_mask:0xf bound_ctrl:1
	v_cvt_pkrtz_f16_f32 v152, -v151, -v151
	v_pk_mul_f16 v153, v152, v138
	v_pk_mul_f16 v154, v152, v139
	v_pk_mul_f16 v155, v152, v140
	v_pk_mul_f16 v156, v152, v141
	v_pk_fma_f16 v153, v215, v142, v153
	v_pk_fma_f16 v154, v215, v143, v154
	v_pk_fma_f16 v155, v215, v144, v155
	v_pk_fma_f16 v156, v215, v145, v156
	v_pk_fma_f16 v127, v127, v130, v153
	v_pk_fma_f16 v126, v126, v131, v154
	v_pk_fma_f16 v125, v125, v132, v155
	v_pk_fma_f16 v124, v124, v133, v156
	v_dot2_f32_f16 v158, v127, v146, 0
	v_dot2_f32_f16 v158, v126, v147, v158
	v_dot2_f32_f16 v158, v125, v148, v158
	v_dot2_f32_f16 v158, v124, v149, v158
	s_waitcnt lgkmcnt(0)
	v_dot2_f32_f16 v151, v127, v72, 0
	v_dot2_f32_f16 v151, v126, v73, v151
	v_dot2_f32_f16 v151, v125, v74, v151
	v_dot2_f32_f16 v151, v124, v75, v151
	ds_read_b128 v[134:137], v114 offset:42112
	ds_read_b128 v[138:141], v114 offset:46208
	ds_read_b128 v[142:145], v114 offset:50304
	v_add_f32_dpp v151, v151, v151 quad_perm:[1,0,3,2] row_mask:0xf bank_mask:0xf bound_ctrl:1
	ds_read_b128 v[130:133], v167 offset:29824
	ds_read_b128 v[146:149], v114 offset:54400
	v_add_f32_dpp v151, v151, v151 quad_perm:[2,3,0,1] row_mask:0xf bank_mask:0xf bound_ctrl:1
	ds_write2st64_b32 v116, v157, v158 offset0:32 offset1:40
	s_nop 0
	v_add_f32_dpp v151, v151, v151 row_half_mirror row_mask:0xf bank_mask:0xf bound_ctrl:1
	v_cvt_pkrtz_f16_f32 v152, -v151, -v151
	v_pk_mul_f16 v153, v152, v68
	v_pk_mul_f16 v154, v152, v69
	v_pk_mul_f16 v155, v152, v70
	v_pk_mul_f16 v156, v152, v71
	v_pk_fma_f16 v153, v216, v64, v153
	v_pk_fma_f16 v154, v216, v65, v154
	v_pk_fma_f16 v155, v216, v66, v155
	v_pk_fma_f16 v156, v216, v67, v156
	v_pk_fma_f16 v127, v127, v60, v153
	v_pk_fma_f16 v126, v126, v61, v154
	v_pk_fma_f16 v125, v125, v62, v155
	v_pk_fma_f16 v124, v124, v63, v156
	v_dot2_f32_f16 v157, v127, v56, 0
	v_dot2_f32_f16 v157, v126, v57, v157
	v_dot2_f32_f16 v157, v125, v58, v157
	v_dot2_f32_f16 v157, v124, v59, v157
	s_waitcnt lgkmcnt(0)
	v_dot2_f32_f16 v151, v127, v134, 0
	v_dot2_f32_f16 v151, v126, v135, v151
	v_dot2_f32_f16 v151, v125, v136, v151
	v_dot2_f32_f16 v151, v124, v137, v151
	ds_read_b128 v[72:75], v114 offset:42240
	ds_read_b128 v[68:71], v114 offset:46336
	ds_read_b128 v[64:67], v114 offset:50432
	v_add_f32_dpp v151, v151, v151 quad_perm:[1,0,3,2] row_mask:0xf bank_mask:0xf bound_ctrl:1
	ds_read_b128 v[60:63], v167 offset:29952
	ds_read_b128 v[56:59], v114 offset:54528
	v_add_f32_dpp v151, v151, v151 quad_perm:[2,3,0,1] row_mask:0xf bank_mask:0xf bound_ctrl:1
	ds_read2st64_b32 v[214:215], v115 offset0:8 offset1:9
	s_nop 0
	v_add_f32_dpp v151, v151, v151 row_half_mirror row_mask:0xf bank_mask:0xf bound_ctrl:1
	v_cvt_pkrtz_f16_f32 v152, -v151, -v151
	v_pk_mul_f16 v153, v152, v138
	v_pk_mul_f16 v154, v152, v139
	v_pk_mul_f16 v155, v152, v140
	v_pk_mul_f16 v156, v152, v141
	v_pk_fma_f16 v153, v217, v142, v153
	v_pk_fma_f16 v154, v217, v143, v154
	v_pk_fma_f16 v155, v217, v144, v155
	v_pk_fma_f16 v156, v217, v145, v156
	v_pk_fma_f16 v127, v127, v130, v153
	v_pk_fma_f16 v126, v126, v131, v154
	v_pk_fma_f16 v125, v125, v132, v155
	v_pk_fma_f16 v124, v124, v133, v156
	v_dot2_f32_f16 v158, v127, v146, 0
	v_dot2_f32_f16 v158, v126, v147, v158
	v_dot2_f32_f16 v158, v125, v148, v158
	v_dot2_f32_f16 v158, v124, v149, v158
	s_waitcnt lgkmcnt(0)
	v_dot2_f32_f16 v151, v127, v72, 0
	v_dot2_f32_f16 v151, v126, v73, v151
	v_dot2_f32_f16 v151, v125, v74, v151
	v_dot2_f32_f16 v151, v124, v75, v151
	ds_read_b128 v[134:137], v114 offset:42368
	ds_read_b128 v[138:141], v114 offset:46464
	ds_read_b128 v[142:145], v114 offset:50560
	v_add_f32_dpp v151, v151, v151 quad_perm:[1,0,3,2] row_mask:0xf bank_mask:0xf bound_ctrl:1
	ds_read_b128 v[130:133], v167 offset:30080
	ds_read_b128 v[146:149], v114 offset:54656
	v_add_f32_dpp v151, v151, v151 quad_perm:[2,3,0,1] row_mask:0xf bank_mask:0xf bound_ctrl:1
	ds_write2st64_b32 v116, v157, v158 offset0:48 offset1:56
	s_nop 0
	v_add_f32_dpp v151, v151, v151 row_half_mirror row_mask:0xf bank_mask:0xf bound_ctrl:1
	v_cvt_pkrtz_f16_f32 v152, -v151, -v151
	v_pk_mul_f16 v153, v152, v68
	v_pk_mul_f16 v154, v152, v69
	v_pk_mul_f16 v155, v152, v70
	v_pk_mul_f16 v156, v152, v71
	v_pk_fma_f16 v153, v214, v64, v153
	v_pk_fma_f16 v154, v214, v65, v154
	v_pk_fma_f16 v155, v214, v66, v155
	v_pk_fma_f16 v156, v214, v67, v156
	v_pk_fma_f16 v127, v127, v60, v153
	v_pk_fma_f16 v126, v126, v61, v154
	v_pk_fma_f16 v125, v125, v62, v155
	v_pk_fma_f16 v124, v124, v63, v156
	v_dot2_f32_f16 v157, v127, v56, 0
	v_dot2_f32_f16 v157, v126, v57, v157
	v_dot2_f32_f16 v157, v125, v58, v157
	v_dot2_f32_f16 v157, v124, v59, v157
	s_waitcnt lgkmcnt(0)
	v_dot2_f32_f16 v151, v127, v134, 0
	v_dot2_f32_f16 v151, v126, v135, v151
	v_dot2_f32_f16 v151, v125, v136, v151
	v_dot2_f32_f16 v151, v124, v137, v151
	ds_read_b128 v[72:75], v114 offset:42496
	ds_read_b128 v[68:71], v114 offset:46592
	ds_read_b128 v[64:67], v114 offset:50688
	v_add_f32_dpp v151, v151, v151 quad_perm:[1,0,3,2] row_mask:0xf bank_mask:0xf bound_ctrl:1
	ds_read_b128 v[60:63], v167 offset:30208
	ds_read_b128 v[56:59], v114 offset:54784
	v_add_f32_dpp v151, v151, v151 quad_perm:[2,3,0,1] row_mask:0xf bank_mask:0xf bound_ctrl:1
	ds_read2st64_b32 v[216:217], v115 offset0:10 offset1:11
	s_nop 0
	v_add_f32_dpp v151, v151, v151 row_half_mirror row_mask:0xf bank_mask:0xf bound_ctrl:1
	v_cvt_pkrtz_f16_f32 v152, -v151, -v151
	v_pk_mul_f16 v153, v152, v138
	v_pk_mul_f16 v154, v152, v139
	v_pk_mul_f16 v155, v152, v140
	v_pk_mul_f16 v156, v152, v141
	v_pk_fma_f16 v153, v215, v142, v153
	v_pk_fma_f16 v154, v215, v143, v154
	v_pk_fma_f16 v155, v215, v144, v155
	v_pk_fma_f16 v156, v215, v145, v156
	v_pk_fma_f16 v127, v127, v130, v153
	v_pk_fma_f16 v126, v126, v131, v154
	v_pk_fma_f16 v125, v125, v132, v155
	v_pk_fma_f16 v124, v124, v133, v156
	v_dot2_f32_f16 v158, v127, v146, 0
	v_dot2_f32_f16 v158, v126, v147, v158
	v_dot2_f32_f16 v158, v125, v148, v158
	v_dot2_f32_f16 v158, v124, v149, v158
	s_waitcnt lgkmcnt(0)
	v_dot2_f32_f16 v151, v127, v72, 0
	v_dot2_f32_f16 v151, v126, v73, v151
	v_dot2_f32_f16 v151, v125, v74, v151
	v_dot2_f32_f16 v151, v124, v75, v151
	ds_read_b128 v[134:137], v114 offset:42624
	ds_read_b128 v[138:141], v114 offset:46720
	ds_read_b128 v[142:145], v114 offset:50816
	v_add_f32_dpp v151, v151, v151 quad_perm:[1,0,3,2] row_mask:0xf bank_mask:0xf bound_ctrl:1
	ds_read_b128 v[130:133], v167 offset:30336
	ds_read_b128 v[146:149], v114 offset:54912
	v_add_f32_dpp v151, v151, v151 quad_perm:[2,3,0,1] row_mask:0xf bank_mask:0xf bound_ctrl:1
	ds_write2st64_b32 v116, v157, v158 offset0:64 offset1:72
	s_nop 0
	v_add_f32_dpp v151, v151, v151 row_half_mirror row_mask:0xf bank_mask:0xf bound_ctrl:1
	v_cvt_pkrtz_f16_f32 v152, -v151, -v151
	v_pk_mul_f16 v153, v152, v68
	v_pk_mul_f16 v154, v152, v69
	v_pk_mul_f16 v155, v152, v70
	v_pk_mul_f16 v156, v152, v71
	v_pk_fma_f16 v153, v216, v64, v153
	v_pk_fma_f16 v154, v216, v65, v154
	v_pk_fma_f16 v155, v216, v66, v155
	v_pk_fma_f16 v156, v216, v67, v156
	v_pk_fma_f16 v127, v127, v60, v153
	v_pk_fma_f16 v126, v126, v61, v154
	v_pk_fma_f16 v125, v125, v62, v155
	v_pk_fma_f16 v124, v124, v63, v156
	v_dot2_f32_f16 v157, v127, v56, 0
	v_dot2_f32_f16 v157, v126, v57, v157
	v_dot2_f32_f16 v157, v125, v58, v157
	v_dot2_f32_f16 v157, v124, v59, v157
	s_waitcnt lgkmcnt(0)
	v_dot2_f32_f16 v151, v127, v134, 0
	v_dot2_f32_f16 v151, v126, v135, v151
	v_dot2_f32_f16 v151, v125, v136, v151
	v_dot2_f32_f16 v151, v124, v137, v151
	ds_read_b128 v[72:75], v114 offset:42752
	ds_read_b128 v[68:71], v114 offset:46848
	ds_read_b128 v[64:67], v114 offset:50944
	v_add_f32_dpp v151, v151, v151 quad_perm:[1,0,3,2] row_mask:0xf bank_mask:0xf bound_ctrl:1
	ds_read_b128 v[60:63], v167 offset:30464
	ds_read_b128 v[56:59], v114 offset:55040
	v_add_f32_dpp v151, v151, v151 quad_perm:[2,3,0,1] row_mask:0xf bank_mask:0xf bound_ctrl:1
	ds_read2st64_b32 v[214:215], v115 offset0:12 offset1:13
	s_nop 0
	v_add_f32_dpp v151, v151, v151 row_half_mirror row_mask:0xf bank_mask:0xf bound_ctrl:1
	v_cvt_pkrtz_f16_f32 v152, -v151, -v151
	v_pk_mul_f16 v153, v152, v138
	v_pk_mul_f16 v154, v152, v139
	v_pk_mul_f16 v155, v152, v140
	v_pk_mul_f16 v156, v152, v141
	v_pk_fma_f16 v153, v217, v142, v153
	v_pk_fma_f16 v154, v217, v143, v154
	v_pk_fma_f16 v155, v217, v144, v155
	v_pk_fma_f16 v156, v217, v145, v156
	v_pk_fma_f16 v127, v127, v130, v153
	v_pk_fma_f16 v126, v126, v131, v154
	v_pk_fma_f16 v125, v125, v132, v155
	v_pk_fma_f16 v124, v124, v133, v156
	v_dot2_f32_f16 v158, v127, v146, 0
	v_dot2_f32_f16 v158, v126, v147, v158
	v_dot2_f32_f16 v158, v125, v148, v158
	v_dot2_f32_f16 v158, v124, v149, v158
	s_waitcnt lgkmcnt(0)
	v_dot2_f32_f16 v151, v127, v72, 0
	v_dot2_f32_f16 v151, v126, v73, v151
	v_dot2_f32_f16 v151, v125, v74, v151
	v_dot2_f32_f16 v151, v124, v75, v151
	ds_read_b128 v[134:137], v114 offset:42880
	ds_read_b128 v[138:141], v114 offset:46976
	ds_read_b128 v[142:145], v114 offset:51072
	v_add_f32_dpp v151, v151, v151 quad_perm:[1,0,3,2] row_mask:0xf bank_mask:0xf bound_ctrl:1
	ds_read_b128 v[130:133], v167 offset:30592
	ds_read_b128 v[146:149], v114 offset:55168
	v_add_f32_dpp v151, v151, v151 quad_perm:[2,3,0,1] row_mask:0xf bank_mask:0xf bound_ctrl:1
	ds_write2st64_b32 v116, v157, v158 offset0:80 offset1:88
	s_nop 0
	v_add_f32_dpp v151, v151, v151 row_half_mirror row_mask:0xf bank_mask:0xf bound_ctrl:1
	v_cvt_pkrtz_f16_f32 v152, -v151, -v151
	v_pk_mul_f16 v153, v152, v68
	v_pk_mul_f16 v154, v152, v69
	v_pk_mul_f16 v155, v152, v70
	v_pk_mul_f16 v156, v152, v71
	v_pk_fma_f16 v153, v214, v64, v153
	v_pk_fma_f16 v154, v214, v65, v154
	v_pk_fma_f16 v155, v214, v66, v155
	v_pk_fma_f16 v156, v214, v67, v156
	v_pk_fma_f16 v127, v127, v60, v153
	v_pk_fma_f16 v126, v126, v61, v154
	v_pk_fma_f16 v125, v125, v62, v155
	v_pk_fma_f16 v124, v124, v63, v156
	v_dot2_f32_f16 v157, v127, v56, 0
	v_dot2_f32_f16 v157, v126, v57, v157
	v_dot2_f32_f16 v157, v125, v58, v157
	v_dot2_f32_f16 v157, v124, v59, v157
	s_waitcnt lgkmcnt(0)
	v_dot2_f32_f16 v151, v127, v134, 0
	v_dot2_f32_f16 v151, v126, v135, v151
	v_dot2_f32_f16 v151, v125, v136, v151
	v_dot2_f32_f16 v151, v124, v137, v151
	ds_read_b128 v[72:75], v114 offset:43008
	ds_read_b128 v[68:71], v114 offset:47104
	ds_read_b128 v[64:67], v114 offset:51200
	v_add_f32_dpp v151, v151, v151 quad_perm:[1,0,3,2] row_mask:0xf bank_mask:0xf bound_ctrl:1
	ds_read_b128 v[60:63], v167 offset:30720
	ds_read_b128 v[56:59], v114 offset:55296
	v_add_f32_dpp v151, v151, v151 quad_perm:[2,3,0,1] row_mask:0xf bank_mask:0xf bound_ctrl:1
	ds_read2st64_b32 v[216:217], v115 offset0:14 offset1:15
	s_nop 0
	v_add_f32_dpp v151, v151, v151 row_half_mirror row_mask:0xf bank_mask:0xf bound_ctrl:1
	v_cvt_pkrtz_f16_f32 v152, -v151, -v151
	v_pk_mul_f16 v153, v152, v138
	v_pk_mul_f16 v154, v152, v139
	v_pk_mul_f16 v155, v152, v140
	v_pk_mul_f16 v156, v152, v141
	v_pk_fma_f16 v153, v215, v142, v153
	v_pk_fma_f16 v154, v215, v143, v154
	v_pk_fma_f16 v155, v215, v144, v155
	v_pk_fma_f16 v156, v215, v145, v156
	v_pk_fma_f16 v127, v127, v130, v153
	v_pk_fma_f16 v126, v126, v131, v154
	v_pk_fma_f16 v125, v125, v132, v155
	v_pk_fma_f16 v124, v124, v133, v156
	v_dot2_f32_f16 v158, v127, v146, 0
	v_dot2_f32_f16 v158, v126, v147, v158
	v_dot2_f32_f16 v158, v125, v148, v158
	v_dot2_f32_f16 v158, v124, v149, v158
	s_waitcnt lgkmcnt(0)
	v_dot2_f32_f16 v151, v127, v72, 0
	v_dot2_f32_f16 v151, v126, v73, v151
	v_dot2_f32_f16 v151, v125, v74, v151
	v_dot2_f32_f16 v151, v124, v75, v151
	ds_read_b128 v[134:137], v114 offset:43136
	ds_read_b128 v[138:141], v114 offset:47232
	ds_read_b128 v[142:145], v114 offset:51328
	v_add_f32_dpp v151, v151, v151 quad_perm:[1,0,3,2] row_mask:0xf bank_mask:0xf bound_ctrl:1
	ds_read_b128 v[130:133], v167 offset:30848
	ds_read_b128 v[146:149], v114 offset:55424
	v_add_f32_dpp v151, v151, v151 quad_perm:[2,3,0,1] row_mask:0xf bank_mask:0xf bound_ctrl:1
	ds_write2st64_b32 v116, v157, v158 offset0:96 offset1:104
	s_nop 0
	v_add_f32_dpp v151, v151, v151 row_half_mirror row_mask:0xf bank_mask:0xf bound_ctrl:1
	v_cvt_pkrtz_f16_f32 v152, -v151, -v151
	v_pk_mul_f16 v153, v152, v68
	v_pk_mul_f16 v154, v152, v69
	v_pk_mul_f16 v155, v152, v70
	v_pk_mul_f16 v156, v152, v71
	v_pk_fma_f16 v153, v216, v64, v153
	v_pk_fma_f16 v154, v216, v65, v154
	v_pk_fma_f16 v155, v216, v66, v155
	v_pk_fma_f16 v156, v216, v67, v156
	v_pk_fma_f16 v127, v127, v60, v153
	v_pk_fma_f16 v126, v126, v61, v154
	v_pk_fma_f16 v125, v125, v62, v155
	v_pk_fma_f16 v124, v124, v63, v156
	v_dot2_f32_f16 v157, v127, v56, 0
	v_dot2_f32_f16 v157, v126, v57, v157
	v_dot2_f32_f16 v157, v125, v58, v157
	v_dot2_f32_f16 v157, v124, v59, v157
	s_waitcnt lgkmcnt(0)
	v_dot2_f32_f16 v151, v127, v134, 0
	v_dot2_f32_f16 v151, v126, v135, v151
	v_dot2_f32_f16 v151, v125, v136, v151
	v_dot2_f32_f16 v151, v124, v137, v151
	s_nop 2
	v_add_f32_dpp v151, v151, v151 quad_perm:[1,0,3,2] row_mask:0xf bank_mask:0xf bound_ctrl:1
	s_nop 1
	v_add_f32_dpp v151, v151, v151 quad_perm:[2,3,0,1] row_mask:0xf bank_mask:0xf bound_ctrl:1
	s_nop 1
	v_add_f32_dpp v151, v151, v151 row_half_mirror row_mask:0xf bank_mask:0xf bound_ctrl:1
	v_cvt_pkrtz_f16_f32 v152, -v151, -v151
	v_pk_mul_f16 v153, v152, v138
	v_pk_mul_f16 v154, v152, v139
	v_pk_mul_f16 v155, v152, v140
	v_pk_mul_f16 v156, v152, v141
	v_pk_fma_f16 v153, v217, v142, v153
	v_pk_fma_f16 v154, v217, v143, v154
	v_pk_fma_f16 v155, v217, v144, v155
	v_pk_fma_f16 v156, v217, v145, v156
	v_pk_fma_f16 v127, v127, v130, v153
	v_pk_fma_f16 v126, v126, v131, v154
	v_pk_fma_f16 v125, v125, v132, v155
	v_pk_fma_f16 v124, v124, v133, v156
	v_dot2_f32_f16 v158, v127, v146, 0
	v_dot2_f32_f16 v158, v126, v147, v158
	v_dot2_f32_f16 v158, v125, v148, v158
	v_dot2_f32_f16 v158, v124, v149, v158
	s_nop 2
	ds_write2st64_b32 v116, v157, v158 offset0:112 offset1:120
	s_xor_b32 s100, s100, 0xe100
	s_cmpk_lg_i32 s30, 0x80
	s_cbranch_scc0 .LBB0_1250
	s_mov_b32 s4, s30
	s_and_saveexec_b64 s[18:19], s[10:11]
	s_cbranch_execnz .LBB0_1229
	s_branch .LBB0_1230
